# SwiGLU epilogue rewritten with fewer VALU ops; first K-iteration waits relaxed past epilogue stores; attention row-max tree via v_max3; MoBA mask copies and -inf prefill removed from hot path
# speedup vs baseline: 1.0062x; 1.0062x over previous
.LBB0_767:
	v_max3_f32 v0, v96, v97, v98
	v_max3_f32 v2, v112, v113, v114
	v_max3_f32 v0, v0, v99, v100
	v_max3_f32 v2, v2, v115, v116
	v_max3_f32 v0, v0, v101, v102
	v_max3_f32 v2, v2, v117, v118
	v_max3_f32 v0, v0, v103, v104
	v_max3_f32 v2, v2, v119, v120
	v_max3_f32 v0, v0, v105, v106
	v_max3_f32 v2, v2, v121, v122
	v_max3_f32 v0, v0, v107, v108
	v_max3_f32 v2, v2, v123, v124
	v_max3_f32 v0, v0, v109, v110
	v_max3_f32 v2, v2, v125, v126
	v_max_f32_e32 v0, v0, v111
	v_max_f32_e32 v2, v2, v127
	v_max3_f32 v3, v64, v65, v66
	v_max3_f32 v4, v80, v81, v82
	v_max3_f32 v3, v3, v67, v68
	v_max3_f32 v4, v4, v83, v84
	v_max3_f32 v3, v3, v69, v70
	v_max3_f32 v4, v4, v85, v86
	v_max3_f32 v3, v3, v71, v72
	v_max3_f32 v4, v4, v87, v88
	v_max3_f32 v3, v3, v73, v74
	v_max3_f32 v4, v4, v89, v90
	v_max3_f32 v3, v3, v75, v76
	v_max3_f32 v4, v4, v91, v92
	v_max3_f32 v3, v3, v77, v78
	v_max3_f32 v4, v4, v93, v94
	v_max_f32_e32 v3, v3, v79
	v_max_f32_e32 v4, v4, v95
	v_max3_f32 v0, v0, v2, v3
	v_max_f32_e32 v0, v0, v4
	v_xor_b32_e32 v2, 32, v241
	v_cmp_lt_i32_e32 vcc, v2, v242
	s_nop 1
	v_cndmask_b32_e32 v2, v241, v2, vcc
	v_lshlrev_b32_e32 v2, 2, v2
	ds_bpermute_b32 v2, v2, v0
	s_waitcnt lgkmcnt(0)
	v_max_f32_e32 v2, v2, v2
	v_max_f32_e32 v0, v0, v2
	v_add_f32_e32 v2, 0x41000000, v208
	v_cmp_gt_f32_e32 vcc, v0, v2
	s_cbranch_vccz .LBB0_769
	v_max_f32_e32 v0, v0, v0
	v_max_f32_e32 v2, v208, v208
	v_max_f32_e32 v2, v2, v0
	v_cmp_neq_f32_e32 vcc, s54, v2
	s_nop 1
	v_cndmask_b32_e32 v0, 0, v2, vcc
	v_sub_f32_e32 v0, v208, v0
	v_exp_f32_e32 v0, v0
	v_mov_b32_e32 v208, v2
	v_pk_mul_f32 v[62:63], v[62:63], v[0:1] op_sel_hi:[1,0]
	v_pk_mul_f32 v[60:61], v[60:61], v[0:1] op_sel_hi:[1,0]
	v_pk_mul_f32 v[58:59], v[58:59], v[0:1] op_sel_hi:[1,0]
	v_pk_mul_f32 v[56:57], v[56:57], v[0:1] op_sel_hi:[1,0]
	v_pk_mul_f32 v[54:55], v[54:55], v[0:1] op_sel_hi:[1,0]
	v_pk_mul_f32 v[52:53], v[52:53], v[0:1] op_sel_hi:[1,0]
	v_pk_mul_f32 v[50:51], v[50:51], v[0:1] op_sel_hi:[1,0]
	v_pk_mul_f32 v[48:49], v[48:49], v[0:1] op_sel_hi:[1,0]
	v_pk_mul_f32 v[46:47], v[46:47], v[0:1] op_sel_hi:[1,0]
	v_pk_mul_f32 v[44:45], v[44:45], v[0:1] op_sel_hi:[1,0]
	v_pk_mul_f32 v[42:43], v[42:43], v[0:1] op_sel_hi:[1,0]
	v_pk_mul_f32 v[40:41], v[40:41], v[0:1] op_sel_hi:[1,0]
	v_pk_mul_f32 v[38:39], v[38:39], v[0:1] op_sel_hi:[1,0]
	v_pk_mul_f32 v[36:37], v[36:37], v[0:1] op_sel_hi:[1,0]
	v_pk_mul_f32 v[34:35], v[34:35], v[0:1] op_sel_hi:[1,0]
	v_pk_mul_f32 v[32:33], v[32:33], v[0:1] op_sel_hi:[1,0]
	v_mul_f32_e32 v225, v225, v0

.LBB0_802:
	s_and_b64 s[0:1], s[4:5], s[10:11]
	s_and_b64 vcc, exec, s[0:1]
	s_cbranch_vccnz .LBB0_797
	s_xor_b64 s[0:1], s[4:5], -1
	s_mul_hi_u32 s4, s88, 0xaaaaaaab
	s_lshr_b32 s89, s4, 1
	s_mul_i32 s89, s89, 0x18000
	v_cndmask_b32_e64 v69, 0, 1, s[0:1]
	v_subrev_u32_e32 v65, s89, v27
	v_subrev_u32_e32 v66, s89, v28
	v_subrev_u32_e32 v67, s89, v29
	v_subrev_u32_e32 v68, s89, v30
	v_cmp_ne_u32_e64 s[4:5], 1, v69
	v_add_u32_e32 v69, s74, v129
	v_mov_b32_e32 v64, 0xff800000
	s_andn2_b64 vcc, exec, s[0:1]
	v_add_u32_e32 v135, v69, v65
	v_add_u32_e32 v134, v69, v66
	v_add_u32_e32 v133, v69, v67
	v_add_u32_e32 v132, v69, v68
	s_cbranch_vccz .Lk0_qk0
	v_mov_b32_e32 v112, 0xff800000
	v_mov_b32_e32 v113, 0xff800000
	v_mov_b32_e32 v114, 0xff800000
	v_mov_b32_e32 v115, 0xff800000
	v_mov_b32_e32 v116, 0xff800000
	v_mov_b32_e32 v117, 0xff800000
	v_mov_b32_e32 v118, 0xff800000
	v_mov_b32_e32 v119, 0xff800000
	v_mov_b32_e32 v120, 0xff800000
	v_mov_b32_e32 v121, 0xff800000
	v_mov_b32_e32 v122, 0xff800000
	v_mov_b32_e32 v123, 0xff800000
	v_mov_b32_e32 v124, 0xff800000
	v_mov_b32_e32 v125, 0xff800000
	v_mov_b32_e32 v126, 0xff800000
	v_mov_b32_e32 v127, 0xff800000
	v_mov_b32_e32 v96, 0xff800000
	v_mov_b32_e32 v97, 0xff800000
	v_mov_b32_e32 v98, 0xff800000
	v_mov_b32_e32 v99, 0xff800000
	v_mov_b32_e32 v100, 0xff800000
	v_mov_b32_e32 v101, 0xff800000
	v_mov_b32_e32 v102, 0xff800000
	v_mov_b32_e32 v103, 0xff800000
	v_mov_b32_e32 v104, 0xff800000
	v_mov_b32_e32 v105, 0xff800000
	v_mov_b32_e32 v106, 0xff800000
	v_mov_b32_e32 v107, 0xff800000
	v_mov_b32_e32 v108, 0xff800000
	v_mov_b32_e32 v109, 0xff800000
	v_mov_b32_e32 v110, 0xff800000
	v_mov_b32_e32 v111, 0xff800000
	s_branch .LBB0_805
.Lk0_qk0:
	ds_read_b128 v[66:69], v135
	ds_read_b128 v[70:73], v135 offset:4096
	ds_read_b128 v[74:77], v134
	ds_read_b128 v[78:81], v134 offset:4096
	ds_read_b128 v[82:85], v133
	ds_read_b128 v[86:89], v133 offset:4096
	ds_read_b128 v[90:93], v132
	ds_read_b128 v[136:139], v132 offset:4096
	s_setprio 1
	s_waitcnt lgkmcnt(0)
	v_mfma_f32_32x32x16_bf16 v[112:127], v[66:69], v[2:5], 0
	v_mfma_f32_32x32x16_bf16 v[96:111], v[70:73], v[2:5], 0
	v_mfma_f32_32x32x16_bf16 v[112:127], v[74:77], v[6:9], v[112:127]
	v_mfma_f32_32x32x16_bf16 v[96:111], v[78:81], v[6:9], v[96:111]
	v_mfma_f32_32x32x16_bf16 v[112:127], v[82:85], v[10:13], v[112:127]
	v_mfma_f32_32x32x16_bf16 v[96:111], v[86:89], v[10:13], v[96:111]
	v_mfma_f32_32x32x16_bf16 v[112:127], v[90:93], v[18:21], v[112:127]
	v_mfma_f32_32x32x16_bf16 v[96:111], v[136:139], v[18:21], v[96:111]
	s_setprio 0
.LBB0_805:
	s_xor_b64 s[10:11], s[10:11], -1
	v_cndmask_b32_e64 v65, 0, 1, s[10:11]
	v_cmp_ne_u32_e64 s[0:1], 1, v65
	s_andn2_b64 vcc, exec, s[10:11]
	s_cbranch_vccz .Lk0_qk1
	v_mov_b32_e32 v65, 0xff800000
	v_mov_b32_e32 v66, 0xff800000
	v_mov_b32_e32 v67, 0xff800000
	v_mov_b32_e32 v68, 0xff800000
	v_mov_b32_e32 v69, 0xff800000
	v_mov_b32_e32 v70, 0xff800000
	v_mov_b32_e32 v71, 0xff800000
	v_mov_b32_e32 v72, 0xff800000
	v_mov_b32_e32 v73, 0xff800000
	v_mov_b32_e32 v74, 0xff800000
	v_mov_b32_e32 v75, 0xff800000
	v_mov_b32_e32 v76, 0xff800000
	v_mov_b32_e32 v77, 0xff800000
	v_mov_b32_e32 v78, 0xff800000
	v_mov_b32_e32 v79, 0xff800000
	v_mov_b32_e32 v80, 0xff800000
	v_mov_b32_e32 v81, 0xff800000
	v_mov_b32_e32 v82, 0xff800000
	v_mov_b32_e32 v83, 0xff800000
	v_mov_b32_e32 v84, 0xff800000
	v_mov_b32_e32 v85, 0xff800000
	v_mov_b32_e32 v86, 0xff800000
	v_mov_b32_e32 v87, 0xff800000
	v_mov_b32_e32 v88, 0xff800000
	v_mov_b32_e32 v89, 0xff800000
	v_mov_b32_e32 v90, 0xff800000
	v_mov_b32_e32 v91, 0xff800000
	v_mov_b32_e32 v92, 0xff800000
	v_mov_b32_e32 v93, 0xff800000
	v_mov_b32_e32 v94, 0xff800000
	v_mov_b32_e32 v95, 0xff800000
	s_branch .LBB0_807
.Lk0_qk1:
	ds_read_b128 v[64:67], v135 offset:8192
	ds_read_b128 v[80:83], v135 offset:12288
	ds_read_b128 v[136:139], v134 offset:8192
	ds_read_b128 v[140:143], v134 offset:12288
	ds_read_b128 v[144:147], v133 offset:8192
	ds_read_b128 v[148:151], v133 offset:12288
	ds_read_b128 v[152:155], v132 offset:8192
	ds_read_b128 v[132:135], v132 offset:12288
	s_setprio 1
	s_waitcnt lgkmcnt(0)
	v_mfma_f32_32x32x16_bf16 v[64:79], v[64:67], v[2:5], 0
	v_mfma_f32_32x32x16_bf16 v[80:95], v[80:83], v[2:5], 0
	v_mfma_f32_32x32x16_bf16 v[64:79], v[136:139], v[6:9], v[64:79]
	v_mfma_f32_32x32x16_bf16 v[80:95], v[140:143], v[6:9], v[80:95]
	v_mfma_f32_32x32x16_bf16 v[64:79], v[144:147], v[10:13], v[64:79]
	v_mfma_f32_32x32x16_bf16 v[80:95], v[148:151], v[10:13], v[80:95]
	v_mfma_f32_32x32x16_bf16 v[64:79], v[152:155], v[18:21], v[64:79]
	v_mfma_f32_32x32x16_bf16 v[80:95], v[132:135], v[18:21], v[80:95]
	s_setprio 0

.LBB0_813:
	s_or_b64 exec, exec, s[10:11]
	s_branch .LBB0_815

.LBB0_821:
	s_or_b64 exec, exec, s[8:9]
	s_branch .LBB0_823

.LBB0_823:
	v_max3_f32 v132, v96, v97, v98
	v_max3_f32 v133, v112, v113, v114
	v_max3_f32 v132, v132, v99, v100
	v_max3_f32 v133, v133, v115, v116
	v_max3_f32 v132, v132, v101, v102
	v_max3_f32 v133, v133, v117, v118
	v_max3_f32 v132, v132, v103, v104
	v_max3_f32 v133, v133, v119, v120
	v_max3_f32 v132, v132, v105, v106
	v_max3_f32 v133, v133, v121, v122
	v_max3_f32 v132, v132, v107, v108
	v_max3_f32 v133, v133, v123, v124
	v_max3_f32 v132, v132, v109, v110
	v_max3_f32 v133, v133, v125, v126
	v_max_f32_e32 v132, v132, v111
	v_max_f32_e32 v133, v133, v127
	v_max3_f32 v134, v64, v65, v66
	v_max3_f32 v135, v80, v81, v82
	v_max3_f32 v134, v134, v67, v68
	v_max3_f32 v135, v135, v83, v84
	v_max3_f32 v134, v134, v69, v70
	v_max3_f32 v135, v135, v85, v86
	v_max3_f32 v134, v134, v71, v72
	v_max3_f32 v135, v135, v87, v88
	v_max3_f32 v134, v134, v73, v74
	v_max3_f32 v135, v135, v89, v90
	v_max3_f32 v134, v134, v75, v76
	v_max3_f32 v135, v135, v91, v92
	v_max3_f32 v134, v134, v77, v78
	v_max3_f32 v135, v135, v93, v94
	v_max_f32_e32 v134, v134, v79
	v_max_f32_e32 v135, v135, v95
	v_max3_f32 v132, v132, v133, v134
	v_max_f32_e32 v132, v132, v135
	v_xor_b32_e32 v133, 32, v241
	v_cmp_lt_i32_e32 vcc, v133, v242
	s_nop 1
	v_cndmask_b32_e32 v133, v241, v133, vcc
	v_lshlrev_b32_e32 v133, 2, v133
	ds_bpermute_b32 v133, v133, v132
	s_waitcnt lgkmcnt(0)
	v_max_f32_e32 v133, v133, v133
	v_max_f32_e32 v132, v132, v133
	v_add_f32_e32 v133, 0x41000000, v131
	v_cmp_gt_f32_e32 vcc, v132, v133
	s_cbranch_vccz .LBB0_825
	v_max_f32_e32 v132, v132, v132
	v_max_f32_e32 v133, v131, v131
	v_max_f32_e32 v133, v133, v132
	v_cmp_neq_f32_e32 vcc, s54, v133
	s_nop 1
	v_cndmask_b32_e32 v132, 0, v133, vcc
	v_sub_f32_e32 v131, v131, v132
	v_exp_f32_e32 v132, v131
	v_mov_b32_e32 v131, v133
	v_pk_mul_f32 v[62:63], v[62:63], v[132:133] op_sel_hi:[1,0]
	v_pk_mul_f32 v[60:61], v[60:61], v[132:133] op_sel_hi:[1,0]
	v_pk_mul_f32 v[58:59], v[58:59], v[132:133] op_sel_hi:[1,0]
	v_pk_mul_f32 v[56:57], v[56:57], v[132:133] op_sel_hi:[1,0]
	v_pk_mul_f32 v[54:55], v[54:55], v[132:133] op_sel_hi:[1,0]
	v_pk_mul_f32 v[52:53], v[52:53], v[132:133] op_sel_hi:[1,0]
	v_pk_mul_f32 v[50:51], v[50:51], v[132:133] op_sel_hi:[1,0]
	v_pk_mul_f32 v[48:49], v[48:49], v[132:133] op_sel_hi:[1,0]
	v_pk_mul_f32 v[46:47], v[46:47], v[132:133] op_sel_hi:[1,0]
	v_pk_mul_f32 v[44:45], v[44:45], v[132:133] op_sel_hi:[1,0]
	v_pk_mul_f32 v[42:43], v[42:43], v[132:133] op_sel_hi:[1,0]
	v_pk_mul_f32 v[40:41], v[40:41], v[132:133] op_sel_hi:[1,0]
	v_pk_mul_f32 v[38:39], v[38:39], v[132:133] op_sel_hi:[1,0]
	v_pk_mul_f32 v[36:37], v[36:37], v[132:133] op_sel_hi:[1,0]
	v_pk_mul_f32 v[34:35], v[34:35], v[132:133] op_sel_hi:[1,0]
	v_pk_mul_f32 v[32:33], v[32:33], v[132:133] op_sel_hi:[1,0]
	v_mul_f32_e32 v130, v130, v132

.LBB0_893:
	s_add_u32 s20, s4, 0xfffc0080
	s_addc_u32 s21, s5, -1
	s_add_i32 s41, 0, 0x10000
	s_cmp_eq_u32 s40, 12
	s_cselect_b32 s23, s15, s21
	s_cselect_b32 s22, s36, s20
	s_cselect_b32 s21, s11, s39
	s_cselect_b32 s20, s37, s38
	s_add_i32 s44, 0, 0x14000
	v_add_u32_e32 v156, s41, v171
	v_add_u32_e32 v164, s44, v171
	ds_read_b128 v[134:137], v156
	ds_read_b128 v[148:151], v156 offset:1024
	ds_read_b128 v[152:155], v156 offset:2048
	ds_read_b128 v[156:159], v156 offset:3072
	ds_read_b128 v[160:163], v164
	ds_read_b128 v[182:185], v164 offset:1024
	ds_read_b128 v[186:189], v164 offset:2048
	ds_read_b128 v[190:193], v164 offset:3072
	v_lshl_add_u64 v[226:227], s[4:5], 0, v[144:145]
	s_add_i32 m0, s26, 0xc000
	ds_read_b128 v[194:197], v175
	ds_read_b128 v[198:201], v175 offset:1024
	ds_read_b128 v[202:205], v175 offset:2048
	ds_read_b128 v[206:209], v175 offset:3072
	ds_read_b128 v[210:213], v175 offset:4096
	ds_read_b128 v[214:217], v175 offset:5120
	ds_read_b128 v[218:221], v175 offset:6144
	ds_read_b128 v[222:225], v175 offset:7168
	global_load_lds_dwordx4 v[226:227], off
	v_lshl_add_u64 v[226:227], s[4:5], 0, v[146:147]
	s_add_i32 m0, s26, 0xe000
	s_nop 0
	global_load_lds_dwordx4 v[226:227], off
	s_cmp_eq_i32 s40, -2
	s_cselect_b32 s98, s2, 0
	s_cmp_lg_u32 s98, 0
	s_cbranch_scc1 .Lg3_relax_w1
	s_waitcnt vmcnt(8)
	s_branch .Lg3_join_w1
.Lg3_relax_w1:
	s_waitcnt vmcnt(16)
.Lg3_join_w1:
	s_waitcnt lgkmcnt(0)
	s_barrier
	s_setprio 1
	s_waitcnt lgkmcnt(0)
	v_mfma_f32_16x16x32_bf16 v[130:133], v[134:137], v[194:197], v[130:133]
	v_mfma_f32_16x16x32_bf16 v[122:125], v[152:155], v[194:197], v[122:125]
	v_mfma_f32_16x16x32_bf16 v[114:117], v[134:137], v[202:205], v[114:117]
	v_mfma_f32_16x16x32_bf16 v[106:109], v[152:155], v[202:205], v[106:109]
	v_mfma_f32_16x16x32_bf16 v[98:101], v[134:137], v[210:213], v[98:101]
	v_mfma_f32_16x16x32_bf16 v[90:93], v[152:155], v[210:213], v[90:93]
	v_mfma_f32_16x16x32_bf16 v[82:85], v[134:137], v[218:221], v[82:85]
	v_mfma_f32_16x16x32_bf16 v[74:77], v[152:155], v[218:221], v[74:77]
	v_mfma_f32_16x16x32_bf16 v[130:133], v[148:151], v[198:201], v[130:133]
	v_mfma_f32_16x16x32_bf16 v[122:125], v[156:159], v[198:201], v[122:125]
	v_mfma_f32_16x16x32_bf16 v[114:117], v[148:151], v[206:209], v[114:117]
	v_mfma_f32_16x16x32_bf16 v[106:109], v[156:159], v[206:209], v[106:109]
	v_mfma_f32_16x16x32_bf16 v[98:101], v[148:151], v[214:217], v[98:101]
	v_mfma_f32_16x16x32_bf16 v[90:93], v[156:159], v[214:217], v[90:93]
	v_mfma_f32_16x16x32_bf16 v[82:85], v[148:151], v[222:225], v[82:85]
	v_mfma_f32_16x16x32_bf16 v[74:77], v[156:159], v[222:225], v[74:77]
	s_setprio 0
	s_setprio 1
	v_mfma_f32_16x16x32_bf16 v[126:129], v[160:163], v[194:197], v[126:129]
	v_mfma_f32_16x16x32_bf16 v[118:121], v[186:189], v[194:197], v[118:121]
	v_mfma_f32_16x16x32_bf16 v[110:113], v[160:163], v[202:205], v[110:113]
	v_mfma_f32_16x16x32_bf16 v[102:105], v[186:189], v[202:205], v[102:105]
	v_mfma_f32_16x16x32_bf16 v[94:97], v[160:163], v[210:213], v[94:97]
	v_mfma_f32_16x16x32_bf16 v[86:89], v[186:189], v[210:213], v[86:89]
	v_mfma_f32_16x16x32_bf16 v[78:81], v[160:163], v[218:221], v[78:81]
	v_mfma_f32_16x16x32_bf16 v[70:73], v[186:189], v[218:221], v[70:73]
	v_mfma_f32_16x16x32_bf16 v[126:129], v[182:185], v[198:201], v[126:129]
	v_mfma_f32_16x16x32_bf16 v[118:121], v[190:193], v[198:201], v[118:121]
	v_mfma_f32_16x16x32_bf16 v[110:113], v[182:185], v[206:209], v[110:113]
	v_mfma_f32_16x16x32_bf16 v[102:105], v[190:193], v[206:209], v[102:105]
	v_mfma_f32_16x16x32_bf16 v[94:97], v[182:185], v[214:217], v[94:97]
	v_mfma_f32_16x16x32_bf16 v[86:89], v[190:193], v[214:217], v[86:89]
	v_mfma_f32_16x16x32_bf16 v[78:81], v[182:185], v[222:225], v[78:81]
	v_mfma_f32_16x16x32_bf16 v[70:73], v[190:193], v[222:225], v[70:73]
	s_setprio 0
	s_barrier
	s_add_i32 s41, s41, s13
	v_lshl_add_u64 v[226:227], s[20:21], 0, v[0:1]
	s_mov_b32 m0, s41
	ds_read_b128 v[194:197], v175 offset:16384
	ds_read_b128 v[198:201], v175 offset:17408
	ds_read_b128 v[202:205], v175 offset:18432
	ds_read_b128 v[206:209], v175 offset:19456
	ds_read_b128 v[210:213], v175 offset:20480
	ds_read_b128 v[214:217], v175 offset:21504
	ds_read_b128 v[218:221], v175 offset:22528
	ds_read_b128 v[222:225], v175 offset:23552
	global_load_lds_dwordx4 v[226:227], off
	s_add_i32 m0, s41, 0x2000
	s_add_u32 s42, s20, 0x40000
	v_lshl_add_u64 v[228:229], s[20:21], 0, v[14:15]
	s_addc_u32 s43, s21, 0
	s_add_i32 s41, s44, s13
	global_load_lds_dwordx4 v[228:229], off
	v_lshl_add_u64 v[230:231], s[42:43], 0, v[0:1]
	s_mov_b32 m0, s41
	v_lshl_add_u64 v[232:233], s[22:23], 0, v[138:139]
	global_load_lds_dwordx4 v[230:231], off
	v_lshl_add_u64 v[230:231], s[42:43], 0, v[14:15]
	s_add_i32 m0, s41, 0x2000
	s_nop 0
	global_load_lds_dwordx4 v[230:231], off
	v_lshl_add_u64 v[230:231], s[22:23], 0, v[140:141]
	s_mov_b32 m0, s26
	s_nop 0
	global_load_lds_dwordx4 v[230:231], off
	s_mov_b32 m0, s27
	s_nop 0
	global_load_lds_dwordx4 v[232:233], off
	s_cmp_eq_i32 s40, -2
	s_cselect_b32 s98, s2, 0
	s_cmp_lg_u32 s98, 0
	s_cbranch_scc1 .Lg3_relax_w2
	s_waitcnt vmcnt(8)
	s_branch .Lg3_join_w2

.Lg3_join_w2:
	s_waitcnt lgkmcnt(0)
	s_barrier
	s_setprio 1
	s_waitcnt lgkmcnt(0)
	v_mfma_f32_16x16x32_bf16 v[66:69], v[134:137], v[194:197], v[66:69]
	v_mfma_f32_16x16x32_bf16 v[58:61], v[152:155], v[194:197], v[58:61]
	v_mfma_f32_16x16x32_bf16 v[50:53], v[134:137], v[202:205], v[50:53]
	v_mfma_f32_16x16x32_bf16 v[42:45], v[152:155], v[202:205], v[42:45]
	v_mfma_f32_16x16x32_bf16 v[34:37], v[134:137], v[210:213], v[34:37]
	v_mfma_f32_16x16x32_bf16 v[26:29], v[152:155], v[210:213], v[26:29]
	v_mfma_f32_16x16x32_bf16 v[18:21], v[134:137], v[218:221], v[18:21]
	v_mfma_f32_16x16x32_bf16 v[6:9], v[152:155], v[218:221], v[6:9]
	v_mfma_f32_16x16x32_bf16 v[66:69], v[148:151], v[198:201], v[66:69]
	v_mfma_f32_16x16x32_bf16 v[58:61], v[156:159], v[198:201], v[58:61]
	v_mfma_f32_16x16x32_bf16 v[50:53], v[148:151], v[206:209], v[50:53]
	v_mfma_f32_16x16x32_bf16 v[42:45], v[156:159], v[206:209], v[42:45]
	v_mfma_f32_16x16x32_bf16 v[34:37], v[148:151], v[214:217], v[34:37]
	v_mfma_f32_16x16x32_bf16 v[26:29], v[156:159], v[214:217], v[26:29]
	v_mfma_f32_16x16x32_bf16 v[18:21], v[148:151], v[222:225], v[18:21]
	v_mfma_f32_16x16x32_bf16 v[6:9], v[156:159], v[222:225], v[6:9]
	s_setprio 0
	s_setprio 1
	v_mfma_f32_16x16x32_bf16 v[62:65], v[160:163], v[194:197], v[62:65]
	v_mfma_f32_16x16x32_bf16 v[54:57], v[186:189], v[194:197], v[54:57]
	v_mfma_f32_16x16x32_bf16 v[46:49], v[160:163], v[202:205], v[46:49]
	v_mfma_f32_16x16x32_bf16 v[38:41], v[186:189], v[202:205], v[38:41]
	v_mfma_f32_16x16x32_bf16 v[30:33], v[160:163], v[210:213], v[30:33]
	v_mfma_f32_16x16x32_bf16 v[22:25], v[186:189], v[210:213], v[22:25]
	v_mfma_f32_16x16x32_bf16 v[10:13], v[160:163], v[218:221], v[10:13]
	v_mfma_f32_16x16x32_bf16 v[2:5], v[186:189], v[218:221], v[2:5]
	v_mfma_f32_16x16x32_bf16 v[62:65], v[182:185], v[198:201], v[62:65]
	v_mfma_f32_16x16x32_bf16 v[54:57], v[190:193], v[198:201], v[54:57]
	v_mfma_f32_16x16x32_bf16 v[46:49], v[182:185], v[206:209], v[46:49]
	v_mfma_f32_16x16x32_bf16 v[38:41], v[190:193], v[206:209], v[38:41]
	v_mfma_f32_16x16x32_bf16 v[30:33], v[182:185], v[214:217], v[30:33]
	v_mfma_f32_16x16x32_bf16 v[22:25], v[190:193], v[214:217], v[22:25]
	v_mfma_f32_16x16x32_bf16 v[10:13], v[182:185], v[222:225], v[10:13]
	v_mfma_f32_16x16x32_bf16 v[2:5], v[190:193], v[222:225], v[2:5]
	s_setprio 0
	s_barrier
	s_add_i32 s41, 0, 0x18000
	s_add_i32 s42, 0, 0x1c000
	v_add_u32_e32 v156, s41, v171
	v_add_u32_e32 v164, s42, v171
	ds_read_b128 v[134:137], v156
	ds_read_b128 v[148:151], v156 offset:1024
	ds_read_b128 v[152:155], v156 offset:2048
	ds_read_b128 v[156:159], v156 offset:3072
	ds_read_b128 v[160:163], v164
	ds_read_b128 v[182:185], v164 offset:1024
	ds_read_b128 v[186:189], v164 offset:2048
	ds_read_b128 v[190:193], v164 offset:3072
	s_add_u32 s22, s22, 0x40000
	s_addc_u32 s23, s23, 0
	s_mov_b32 m0, s28
	v_lshl_add_u64 v[234:235], s[22:23], 0, v[140:141]
	ds_read_b128 v[194:197], v175 offset:32768
	ds_read_b128 v[198:201], v175 offset:33792
	ds_read_b128 v[202:205], v175 offset:34816
	ds_read_b128 v[206:209], v175 offset:35840
	ds_read_b128 v[210:213], v175 offset:36864
	ds_read_b128 v[214:217], v175 offset:37888
	ds_read_b128 v[218:221], v175 offset:38912
	ds_read_b128 v[222:225], v175 offset:39936
	global_load_lds_dwordx4 v[234:235], off
	v_lshl_add_u64 v[234:235], s[22:23], 0, v[138:139]
	s_mov_b32 m0, s29
	s_nop 0
	global_load_lds_dwordx4 v[234:235], off
	s_waitcnt vmcnt(8)
	s_waitcnt lgkmcnt(0)
	s_barrier
	s_setprio 1
	s_waitcnt lgkmcnt(0)
	v_mfma_f32_16x16x32_bf16 v[130:133], v[134:137], v[194:197], v[130:133]
	v_mfma_f32_16x16x32_bf16 v[122:125], v[152:155], v[194:197], v[122:125]
	v_mfma_f32_16x16x32_bf16 v[114:117], v[134:137], v[202:205], v[114:117]
	v_mfma_f32_16x16x32_bf16 v[106:109], v[152:155], v[202:205], v[106:109]
	v_mfma_f32_16x16x32_bf16 v[98:101], v[134:137], v[210:213], v[98:101]
	v_mfma_f32_16x16x32_bf16 v[90:93], v[152:155], v[210:213], v[90:93]
	v_mfma_f32_16x16x32_bf16 v[82:85], v[134:137], v[218:221], v[82:85]
	v_mfma_f32_16x16x32_bf16 v[74:77], v[152:155], v[218:221], v[74:77]
	v_mfma_f32_16x16x32_bf16 v[130:133], v[148:151], v[198:201], v[130:133]
	v_mfma_f32_16x16x32_bf16 v[122:125], v[156:159], v[198:201], v[122:125]
	v_mfma_f32_16x16x32_bf16 v[114:117], v[148:151], v[206:209], v[114:117]
	v_mfma_f32_16x16x32_bf16 v[106:109], v[156:159], v[206:209], v[106:109]
	v_mfma_f32_16x16x32_bf16 v[98:101], v[148:151], v[214:217], v[98:101]
	v_mfma_f32_16x16x32_bf16 v[90:93], v[156:159], v[214:217], v[90:93]
	v_mfma_f32_16x16x32_bf16 v[82:85], v[148:151], v[222:225], v[82:85]
	v_mfma_f32_16x16x32_bf16 v[74:77], v[156:159], v[222:225], v[74:77]
	s_setprio 0
	s_setprio 1
	v_mfma_f32_16x16x32_bf16 v[126:129], v[160:163], v[194:197], v[126:129]
	v_mfma_f32_16x16x32_bf16 v[118:121], v[186:189], v[194:197], v[118:121]
	v_mfma_f32_16x16x32_bf16 v[110:113], v[160:163], v[202:205], v[110:113]
	v_mfma_f32_16x16x32_bf16 v[102:105], v[186:189], v[202:205], v[102:105]
	v_mfma_f32_16x16x32_bf16 v[94:97], v[160:163], v[210:213], v[94:97]
	v_mfma_f32_16x16x32_bf16 v[86:89], v[186:189], v[210:213], v[86:89]
	v_mfma_f32_16x16x32_bf16 v[78:81], v[160:163], v[218:221], v[78:81]
	v_mfma_f32_16x16x32_bf16 v[70:73], v[186:189], v[218:221], v[70:73]
	v_mfma_f32_16x16x32_bf16 v[126:129], v[182:185], v[198:201], v[126:129]
	v_mfma_f32_16x16x32_bf16 v[118:121], v[190:193], v[198:201], v[118:121]
	v_mfma_f32_16x16x32_bf16 v[110:113], v[182:185], v[206:209], v[110:113]
	v_mfma_f32_16x16x32_bf16 v[102:105], v[190:193], v[206:209], v[102:105]
	v_mfma_f32_16x16x32_bf16 v[94:97], v[182:185], v[214:217], v[94:97]
	v_mfma_f32_16x16x32_bf16 v[86:89], v[190:193], v[214:217], v[86:89]
	v_mfma_f32_16x16x32_bf16 v[78:81], v[182:185], v[222:225], v[78:81]
	v_mfma_f32_16x16x32_bf16 v[70:73], v[190:193], v[222:225], v[70:73]
	s_setprio 0
	s_barrier
	s_add_i32 s22, s41, s13
	v_lshl_add_u64 v[226:227], v[226:227], 0, s[92:93]
	s_mov_b32 m0, s22
	ds_read_b128 v[194:197], v175 offset:49152
	ds_read_b128 v[198:201], v175 offset:50176
	ds_read_b128 v[202:205], v175 offset:51200
	ds_read_b128 v[206:209], v175 offset:52224
	ds_read_b128 v[210:213], v175 offset:53248
	ds_read_b128 v[214:217], v175 offset:54272
	ds_read_b128 v[218:221], v175 offset:55296
	ds_read_b128 v[222:225], v175 offset:56320
	global_load_lds_dwordx4 v[226:227], off
	s_add_i32 m0, s22, 0x2000
	s_add_u32 s20, s20, 0x40080
	v_lshl_add_u64 v[226:227], v[228:229], 0, s[92:93]
	s_addc_u32 s21, s21, 0
	s_add_i32 s22, s42, s13
	global_load_lds_dwordx4 v[226:227], off
	v_lshl_add_u64 v[226:227], s[20:21], 0, v[0:1]
	s_mov_b32 m0, s22
	s_nop 0
	global_load_lds_dwordx4 v[226:227], off
	v_lshl_add_u64 v[226:227], s[20:21], 0, v[14:15]
	s_add_i32 m0, s22, 0x2000
	s_nop 0
	global_load_lds_dwordx4 v[226:227], off
	v_lshl_add_u64 v[226:227], v[230:231], 0, s[92:93]
	s_mov_b32 m0, s30
	s_nop 0
	global_load_lds_dwordx4 v[226:227], off
	v_lshl_add_u64 v[226:227], v[232:233], 0, s[92:93]
	s_mov_b32 m0, s31
	s_nop 0
	global_load_lds_dwordx4 v[226:227], off
	s_waitcnt vmcnt(8)
	s_waitcnt lgkmcnt(0)
	s_barrier
	s_setprio 1
	s_waitcnt lgkmcnt(0)
	v_mfma_f32_16x16x32_bf16 v[66:69], v[134:137], v[194:197], v[66:69]
	v_mfma_f32_16x16x32_bf16 v[58:61], v[152:155], v[194:197], v[58:61]
	v_mfma_f32_16x16x32_bf16 v[50:53], v[134:137], v[202:205], v[50:53]
	v_mfma_f32_16x16x32_bf16 v[42:45], v[152:155], v[202:205], v[42:45]
	v_mfma_f32_16x16x32_bf16 v[34:37], v[134:137], v[210:213], v[34:37]
	v_mfma_f32_16x16x32_bf16 v[26:29], v[152:155], v[210:213], v[26:29]
	v_mfma_f32_16x16x32_bf16 v[18:21], v[134:137], v[218:221], v[18:21]
	v_mfma_f32_16x16x32_bf16 v[6:9], v[152:155], v[218:221], v[6:9]
	v_mfma_f32_16x16x32_bf16 v[66:69], v[148:151], v[198:201], v[66:69]
	v_mfma_f32_16x16x32_bf16 v[58:61], v[156:159], v[198:201], v[58:61]
	v_mfma_f32_16x16x32_bf16 v[50:53], v[148:151], v[206:209], v[50:53]
	v_mfma_f32_16x16x32_bf16 v[42:45], v[156:159], v[206:209], v[42:45]
	v_mfma_f32_16x16x32_bf16 v[34:37], v[148:151], v[214:217], v[34:37]
	v_mfma_f32_16x16x32_bf16 v[26:29], v[156:159], v[214:217], v[26:29]
	v_mfma_f32_16x16x32_bf16 v[18:21], v[148:151], v[222:225], v[18:21]
	v_mfma_f32_16x16x32_bf16 v[6:9], v[156:159], v[222:225], v[6:9]
	s_setprio 0
	s_setprio 1
	v_mfma_f32_16x16x32_bf16 v[62:65], v[160:163], v[194:197], v[62:65]
	v_mfma_f32_16x16x32_bf16 v[54:57], v[186:189], v[194:197], v[54:57]
	v_mfma_f32_16x16x32_bf16 v[46:49], v[160:163], v[202:205], v[46:49]
	v_mfma_f32_16x16x32_bf16 v[38:41], v[186:189], v[202:205], v[38:41]
	v_mfma_f32_16x16x32_bf16 v[30:33], v[160:163], v[210:213], v[30:33]
	v_mfma_f32_16x16x32_bf16 v[22:25], v[186:189], v[210:213], v[22:25]
	v_mfma_f32_16x16x32_bf16 v[10:13], v[160:163], v[218:221], v[10:13]
	v_mfma_f32_16x16x32_bf16 v[2:5], v[186:189], v[218:221], v[2:5]
	v_mfma_f32_16x16x32_bf16 v[62:65], v[182:185], v[198:201], v[62:65]
	v_mfma_f32_16x16x32_bf16 v[54:57], v[190:193], v[198:201], v[54:57]
	v_mfma_f32_16x16x32_bf16 v[46:49], v[182:185], v[206:209], v[46:49]
	v_mfma_f32_16x16x32_bf16 v[38:41], v[190:193], v[206:209], v[38:41]
	v_mfma_f32_16x16x32_bf16 v[30:33], v[182:185], v[214:217], v[30:33]
	v_mfma_f32_16x16x32_bf16 v[22:25], v[190:193], v[214:217], v[22:25]
	v_mfma_f32_16x16x32_bf16 v[10:13], v[182:185], v[222:225], v[10:13]
	v_mfma_f32_16x16x32_bf16 v[2:5], v[190:193], v[222:225], v[2:5]
	s_setprio 0
	s_barrier
	s_add_i32 s40, s40, 2
	s_add_u32 s4, s4, 0x100
	s_addc_u32 s5, s5, 0
	s_add_u32 s38, s38, 0x100
	s_addc_u32 s39, s39, 0
	s_cmp_gt_u32 s40, 13
	s_cbranch_scc0 .LBB0_893
	s_and_b64 vcc, exec, s[8:9]
	s_cbranch_vccz .LBB0_896
	s_barrier

.LBB0_900:
	s_waitcnt lgkmcnt(0)
	v_lshl_or_b32 v136, s35, 7, v173
	v_ashrrev_i32_e32 v137, 31, v136
	v_lshl_add_u64 v[136:137], v[136:137], 1, s[66:67]
	v_mul_f32_e32 v188, 0xbfb8aa3b, v172
	v_mul_f32_e32 v190, v172, v172
	v_pk_mul_f32 v[200:201], v[130:131], v[188:189] op_sel_hi:[1,0]
	v_pk_mul_f32 v[202:203], v[132:133], v[188:189] op_sel_hi:[1,0]
	v_pk_mul_f32 v[204:205], v[122:123], v[188:189] op_sel_hi:[1,0]
	v_pk_mul_f32 v[206:207], v[124:125], v[188:189] op_sel_hi:[1,0]
	v_exp_f32_e32 v200, v200
	v_exp_f32_e32 v201, v201
	v_exp_f32_e32 v202, v202
	v_exp_f32_e32 v203, v203
	v_exp_f32_e32 v204, v204
	v_exp_f32_e32 v205, v205
	v_exp_f32_e32 v206, v206
	v_exp_f32_e32 v207, v207
	v_pk_mul_f32 v[130:131], v[130:131], v[126:127]
	v_pk_mul_f32 v[132:133], v[132:133], v[128:129]
	v_pk_mul_f32 v[122:123], v[122:123], v[118:119]
	v_pk_mul_f32 v[124:125], v[124:125], v[120:121]
	v_add_f32_e32 v200, 1.0, v200
	v_add_f32_e32 v201, 1.0, v201
	v_add_f32_e32 v202, 1.0, v202
	v_add_f32_e32 v203, 1.0, v203
	v_add_f32_e32 v204, 1.0, v204
	v_add_f32_e32 v205, 1.0, v205
	v_add_f32_e32 v206, 1.0, v206
	v_add_f32_e32 v207, 1.0, v207
	v_rcp_f32_e32 v200, v200
	v_rcp_f32_e32 v201, v201
	v_rcp_f32_e32 v202, v202
	v_rcp_f32_e32 v203, v203
	v_rcp_f32_e32 v204, v204
	v_rcp_f32_e32 v205, v205
	v_rcp_f32_e32 v206, v206
	v_rcp_f32_e32 v207, v207
	v_pk_mul_f32 v[130:131], v[130:131], v[190:191] op_sel_hi:[1,0]
	v_pk_mul_f32 v[132:133], v[132:133], v[190:191] op_sel_hi:[1,0]
	v_pk_mul_f32 v[122:123], v[122:123], v[190:191] op_sel_hi:[1,0]
	v_pk_mul_f32 v[124:125], v[124:125], v[190:191] op_sel_hi:[1,0]
	v_mad_u64_u32 v[196:197], s[2:3], v162, s78, v[136:137]
	v_pk_mul_f32 v[130:131], v[130:131], v[200:201]
	v_pk_mul_f32 v[132:133], v[132:133], v[202:203]
	v_pk_mul_f32 v[122:123], v[122:123], v[204:205]
	v_pk_mul_f32 v[124:125], v[124:125], v[206:207]
	v_cvt_pk_bf16_f32 v192, v130, v131
	v_cvt_pk_bf16_f32 v193, v132, v133
	v_cvt_pk_bf16_f32 v194, v122, v123
	v_cvt_pk_bf16_f32 v195, v124, v125
	global_store_dwordx4 v[196:197], v[192:195], off
	v_mul_f32_e32 v188, 0xbfb8aa3b, v170
	v_mul_f32_e32 v190, v170, v170
	v_pk_mul_f32 v[200:201], v[114:115], v[188:189] op_sel_hi:[1,0]
	v_pk_mul_f32 v[202:203], v[116:117], v[188:189] op_sel_hi:[1,0]
	v_pk_mul_f32 v[204:205], v[106:107], v[188:189] op_sel_hi:[1,0]
	v_pk_mul_f32 v[206:207], v[108:109], v[188:189] op_sel_hi:[1,0]
	v_exp_f32_e32 v200, v200
	v_exp_f32_e32 v201, v201
	v_exp_f32_e32 v202, v202
	v_exp_f32_e32 v203, v203
	v_exp_f32_e32 v204, v204
	v_exp_f32_e32 v205, v205
	v_exp_f32_e32 v206, v206
	v_exp_f32_e32 v207, v207
	v_pk_mul_f32 v[114:115], v[114:115], v[110:111]
	v_pk_mul_f32 v[116:117], v[116:117], v[112:113]
	v_pk_mul_f32 v[106:107], v[106:107], v[102:103]
	v_pk_mul_f32 v[108:109], v[108:109], v[104:105]
	v_add_f32_e32 v200, 1.0, v200
	v_add_f32_e32 v201, 1.0, v201
	v_add_f32_e32 v202, 1.0, v202
	v_add_f32_e32 v203, 1.0, v203
	v_add_f32_e32 v204, 1.0, v204
	v_add_f32_e32 v205, 1.0, v205
	v_add_f32_e32 v206, 1.0, v206
	v_add_f32_e32 v207, 1.0, v207
	v_rcp_f32_e32 v200, v200
	v_rcp_f32_e32 v201, v201
	v_rcp_f32_e32 v202, v202
	v_rcp_f32_e32 v203, v203
	v_rcp_f32_e32 v204, v204
	v_rcp_f32_e32 v205, v205
	v_rcp_f32_e32 v206, v206
	v_rcp_f32_e32 v207, v207
	v_pk_mul_f32 v[114:115], v[114:115], v[190:191] op_sel_hi:[1,0]
	v_pk_mul_f32 v[116:117], v[116:117], v[190:191] op_sel_hi:[1,0]
	v_pk_mul_f32 v[106:107], v[106:107], v[190:191] op_sel_hi:[1,0]
	v_pk_mul_f32 v[108:109], v[108:109], v[190:191] op_sel_hi:[1,0]
	v_mad_u64_u32 v[196:197], s[2:3], v160, s78, v[136:137]
	v_pk_mul_f32 v[114:115], v[114:115], v[200:201]
	v_pk_mul_f32 v[116:117], v[116:117], v[202:203]
	v_pk_mul_f32 v[106:107], v[106:107], v[204:205]
	v_pk_mul_f32 v[108:109], v[108:109], v[206:207]
	v_cvt_pk_bf16_f32 v192, v114, v115
	v_cvt_pk_bf16_f32 v193, v116, v117
	v_cvt_pk_bf16_f32 v194, v106, v107
	v_cvt_pk_bf16_f32 v195, v108, v109
	global_store_dwordx4 v[196:197], v[192:195], off
	v_mul_f32_e32 v188, 0xbfb8aa3b, v168
	v_mul_f32_e32 v190, v168, v168
	v_pk_mul_f32 v[200:201], v[98:99], v[188:189] op_sel_hi:[1,0]
	v_pk_mul_f32 v[202:203], v[100:101], v[188:189] op_sel_hi:[1,0]
	v_pk_mul_f32 v[204:205], v[90:91], v[188:189] op_sel_hi:[1,0]
	v_pk_mul_f32 v[206:207], v[92:93], v[188:189] op_sel_hi:[1,0]
	v_exp_f32_e32 v200, v200
	v_exp_f32_e32 v201, v201
	v_exp_f32_e32 v202, v202
	v_exp_f32_e32 v203, v203
	v_exp_f32_e32 v204, v204
	v_exp_f32_e32 v205, v205
	v_exp_f32_e32 v206, v206
	v_exp_f32_e32 v207, v207
	v_pk_mul_f32 v[98:99], v[98:99], v[94:95]
	v_pk_mul_f32 v[100:101], v[100:101], v[96:97]
	v_pk_mul_f32 v[90:91], v[90:91], v[86:87]
	v_pk_mul_f32 v[92:93], v[92:93], v[88:89]
	v_add_f32_e32 v200, 1.0, v200
	v_add_f32_e32 v201, 1.0, v201
	v_add_f32_e32 v202, 1.0, v202
	v_add_f32_e32 v203, 1.0, v203
	v_add_f32_e32 v204, 1.0, v204
	v_add_f32_e32 v205, 1.0, v205
	v_add_f32_e32 v206, 1.0, v206
	v_add_f32_e32 v207, 1.0, v207
	v_rcp_f32_e32 v200, v200
	v_rcp_f32_e32 v201, v201
	v_rcp_f32_e32 v202, v202
	v_rcp_f32_e32 v203, v203
	v_rcp_f32_e32 v204, v204
	v_rcp_f32_e32 v205, v205
	v_rcp_f32_e32 v206, v206
	v_rcp_f32_e32 v207, v207
	v_pk_mul_f32 v[98:99], v[98:99], v[190:191] op_sel_hi:[1,0]
	v_pk_mul_f32 v[100:101], v[100:101], v[190:191] op_sel_hi:[1,0]
	v_pk_mul_f32 v[90:91], v[90:91], v[190:191] op_sel_hi:[1,0]
	v_pk_mul_f32 v[92:93], v[92:93], v[190:191] op_sel_hi:[1,0]
	v_mad_u64_u32 v[196:197], s[2:3], v158, s78, v[136:137]
	v_pk_mul_f32 v[98:99], v[98:99], v[200:201]
	v_pk_mul_f32 v[100:101], v[100:101], v[202:203]
	v_pk_mul_f32 v[90:91], v[90:91], v[204:205]
	v_pk_mul_f32 v[92:93], v[92:93], v[206:207]
	v_cvt_pk_bf16_f32 v192, v98, v99
	v_cvt_pk_bf16_f32 v193, v100, v101
	v_cvt_pk_bf16_f32 v194, v90, v91
	v_cvt_pk_bf16_f32 v195, v92, v93
	global_store_dwordx4 v[196:197], v[192:195], off
	v_mul_f32_e32 v188, 0xbfb8aa3b, v164
	v_mul_f32_e32 v190, v164, v164
	v_pk_mul_f32 v[200:201], v[82:83], v[188:189] op_sel_hi:[1,0]
	v_pk_mul_f32 v[202:203], v[84:85], v[188:189] op_sel_hi:[1,0]
	v_pk_mul_f32 v[204:205], v[74:75], v[188:189] op_sel_hi:[1,0]
	v_pk_mul_f32 v[206:207], v[76:77], v[188:189] op_sel_hi:[1,0]
	v_exp_f32_e32 v200, v200
	v_exp_f32_e32 v201, v201
	v_exp_f32_e32 v202, v202
	v_exp_f32_e32 v203, v203
	v_exp_f32_e32 v204, v204
	v_exp_f32_e32 v205, v205
	v_exp_f32_e32 v206, v206
	v_exp_f32_e32 v207, v207
	v_pk_mul_f32 v[82:83], v[82:83], v[78:79]
	v_pk_mul_f32 v[84:85], v[84:85], v[80:81]
	v_pk_mul_f32 v[74:75], v[74:75], v[70:71]
	v_pk_mul_f32 v[76:77], v[76:77], v[72:73]
	v_add_f32_e32 v200, 1.0, v200
	v_add_f32_e32 v201, 1.0, v201
	v_add_f32_e32 v202, 1.0, v202
	v_add_f32_e32 v203, 1.0, v203
	v_add_f32_e32 v204, 1.0, v204
	v_add_f32_e32 v205, 1.0, v205
	v_add_f32_e32 v206, 1.0, v206
	v_add_f32_e32 v207, 1.0, v207
	v_rcp_f32_e32 v200, v200
	v_rcp_f32_e32 v201, v201
	v_rcp_f32_e32 v202, v202
	v_rcp_f32_e32 v203, v203
	v_rcp_f32_e32 v204, v204
	v_rcp_f32_e32 v205, v205
	v_rcp_f32_e32 v206, v206
	v_rcp_f32_e32 v207, v207
	v_pk_mul_f32 v[82:83], v[82:83], v[190:191] op_sel_hi:[1,0]
	v_pk_mul_f32 v[84:85], v[84:85], v[190:191] op_sel_hi:[1,0]
	v_pk_mul_f32 v[74:75], v[74:75], v[190:191] op_sel_hi:[1,0]
	v_pk_mul_f32 v[76:77], v[76:77], v[190:191] op_sel_hi:[1,0]
	v_mad_u64_u32 v[196:197], s[2:3], v156, s78, v[136:137]
	v_pk_mul_f32 v[82:83], v[82:83], v[200:201]
	v_pk_mul_f32 v[84:85], v[84:85], v[202:203]
	v_pk_mul_f32 v[74:75], v[74:75], v[204:205]
	v_pk_mul_f32 v[76:77], v[76:77], v[206:207]
	v_cvt_pk_bf16_f32 v192, v82, v83
	v_cvt_pk_bf16_f32 v193, v84, v85
	v_cvt_pk_bf16_f32 v194, v74, v75
	v_cvt_pk_bf16_f32 v195, v76, v77
	global_store_dwordx4 v[196:197], v[192:195], off
	v_mul_f32_e32 v188, 0xbfb8aa3b, v166
	v_mul_f32_e32 v190, v166, v166
	v_pk_mul_f32 v[200:201], v[66:67], v[188:189] op_sel_hi:[1,0]
	v_pk_mul_f32 v[202:203], v[68:69], v[188:189] op_sel_hi:[1,0]
	v_pk_mul_f32 v[204:205], v[58:59], v[188:189] op_sel_hi:[1,0]
	v_pk_mul_f32 v[206:207], v[60:61], v[188:189] op_sel_hi:[1,0]
	v_exp_f32_e32 v200, v200
	v_exp_f32_e32 v201, v201
	v_exp_f32_e32 v202, v202
	v_exp_f32_e32 v203, v203
	v_exp_f32_e32 v204, v204
	v_exp_f32_e32 v205, v205
	v_exp_f32_e32 v206, v206
	v_exp_f32_e32 v207, v207
	v_pk_mul_f32 v[66:67], v[66:67], v[62:63]
	v_pk_mul_f32 v[68:69], v[68:69], v[64:65]
	v_pk_mul_f32 v[58:59], v[58:59], v[54:55]
	v_pk_mul_f32 v[60:61], v[60:61], v[56:57]
	v_add_f32_e32 v200, 1.0, v200
	v_add_f32_e32 v201, 1.0, v201
	v_add_f32_e32 v202, 1.0, v202
	v_add_f32_e32 v203, 1.0, v203
	v_add_f32_e32 v204, 1.0, v204
	v_add_f32_e32 v205, 1.0, v205
	v_add_f32_e32 v206, 1.0, v206
	v_add_f32_e32 v207, 1.0, v207
	v_rcp_f32_e32 v200, v200
	v_rcp_f32_e32 v201, v201
	v_rcp_f32_e32 v202, v202
	v_rcp_f32_e32 v203, v203
	v_rcp_f32_e32 v204, v204
	v_rcp_f32_e32 v205, v205
	v_rcp_f32_e32 v206, v206
	v_rcp_f32_e32 v207, v207
	v_pk_mul_f32 v[66:67], v[66:67], v[190:191] op_sel_hi:[1,0]
	v_pk_mul_f32 v[68:69], v[68:69], v[190:191] op_sel_hi:[1,0]
	v_pk_mul_f32 v[58:59], v[58:59], v[190:191] op_sel_hi:[1,0]
	v_pk_mul_f32 v[60:61], v[60:61], v[190:191] op_sel_hi:[1,0]
	v_mad_u64_u32 v[196:197], s[2:3], v154, s78, v[136:137]
	v_pk_mul_f32 v[66:67], v[66:67], v[200:201]
	v_pk_mul_f32 v[68:69], v[68:69], v[202:203]
	v_pk_mul_f32 v[58:59], v[58:59], v[204:205]
	v_pk_mul_f32 v[60:61], v[60:61], v[206:207]
	v_cvt_pk_bf16_f32 v192, v66, v67
	v_cvt_pk_bf16_f32 v193, v68, v69
	v_cvt_pk_bf16_f32 v194, v58, v59
	v_cvt_pk_bf16_f32 v195, v60, v61
	global_store_dwordx4 v[196:197], v[192:195], off
	v_mul_f32_e32 v188, 0xbfb8aa3b, v174
	v_mul_f32_e32 v190, v174, v174
	v_pk_mul_f32 v[200:201], v[50:51], v[188:189] op_sel_hi:[1,0]
	v_pk_mul_f32 v[202:203], v[52:53], v[188:189] op_sel_hi:[1,0]
	v_pk_mul_f32 v[204:205], v[42:43], v[188:189] op_sel_hi:[1,0]
	v_pk_mul_f32 v[206:207], v[44:45], v[188:189] op_sel_hi:[1,0]
	v_exp_f32_e32 v200, v200
	v_exp_f32_e32 v201, v201
	v_exp_f32_e32 v202, v202
	v_exp_f32_e32 v203, v203
	v_exp_f32_e32 v204, v204
	v_exp_f32_e32 v205, v205
	v_exp_f32_e32 v206, v206
	v_exp_f32_e32 v207, v207
	v_pk_mul_f32 v[50:51], v[50:51], v[46:47]
	v_pk_mul_f32 v[52:53], v[52:53], v[48:49]
	v_pk_mul_f32 v[42:43], v[42:43], v[38:39]
	v_pk_mul_f32 v[44:45], v[44:45], v[40:41]
	v_add_f32_e32 v200, 1.0, v200
	v_add_f32_e32 v201, 1.0, v201
	v_add_f32_e32 v202, 1.0, v202
	v_add_f32_e32 v203, 1.0, v203
	v_add_f32_e32 v204, 1.0, v204
	v_add_f32_e32 v205, 1.0, v205
	v_add_f32_e32 v206, 1.0, v206
	v_add_f32_e32 v207, 1.0, v207
	v_rcp_f32_e32 v200, v200
	v_rcp_f32_e32 v201, v201
	v_rcp_f32_e32 v202, v202
	v_rcp_f32_e32 v203, v203
	v_rcp_f32_e32 v204, v204
	v_rcp_f32_e32 v205, v205
	v_rcp_f32_e32 v206, v206
	v_rcp_f32_e32 v207, v207
	v_pk_mul_f32 v[50:51], v[50:51], v[190:191] op_sel_hi:[1,0]
	v_pk_mul_f32 v[52:53], v[52:53], v[190:191] op_sel_hi:[1,0]
	v_pk_mul_f32 v[42:43], v[42:43], v[190:191] op_sel_hi:[1,0]
	v_pk_mul_f32 v[44:45], v[44:45], v[190:191] op_sel_hi:[1,0]
	v_mad_u64_u32 v[196:197], s[2:3], v152, s78, v[136:137]
	v_pk_mul_f32 v[50:51], v[50:51], v[200:201]
	v_pk_mul_f32 v[52:53], v[52:53], v[202:203]
	v_pk_mul_f32 v[42:43], v[42:43], v[204:205]
	v_pk_mul_f32 v[44:45], v[44:45], v[206:207]
	v_cvt_pk_bf16_f32 v192, v50, v51
	v_cvt_pk_bf16_f32 v193, v52, v53
	v_cvt_pk_bf16_f32 v194, v42, v43
	v_cvt_pk_bf16_f32 v195, v44, v45
	global_store_dwordx4 v[196:197], v[192:195], off
	v_mul_f32_e32 v188, 0xbfb8aa3b, v182
	v_mul_f32_e32 v190, v182, v182
	v_pk_mul_f32 v[200:201], v[34:35], v[188:189] op_sel_hi:[1,0]
	v_pk_mul_f32 v[202:203], v[36:37], v[188:189] op_sel_hi:[1,0]
	v_pk_mul_f32 v[204:205], v[26:27], v[188:189] op_sel_hi:[1,0]
	v_pk_mul_f32 v[206:207], v[28:29], v[188:189] op_sel_hi:[1,0]
	v_exp_f32_e32 v200, v200
	v_exp_f32_e32 v201, v201
	v_exp_f32_e32 v202, v202
	v_exp_f32_e32 v203, v203
	v_exp_f32_e32 v204, v204
	v_exp_f32_e32 v205, v205
	v_exp_f32_e32 v206, v206
	v_exp_f32_e32 v207, v207
	v_pk_mul_f32 v[34:35], v[34:35], v[30:31]
	v_pk_mul_f32 v[36:37], v[36:37], v[32:33]
	v_pk_mul_f32 v[26:27], v[26:27], v[22:23]
	v_pk_mul_f32 v[28:29], v[28:29], v[24:25]
	v_add_f32_e32 v200, 1.0, v200
	v_add_f32_e32 v201, 1.0, v201
	v_add_f32_e32 v202, 1.0, v202
	v_add_f32_e32 v203, 1.0, v203
	v_add_f32_e32 v204, 1.0, v204
	v_add_f32_e32 v205, 1.0, v205
	v_add_f32_e32 v206, 1.0, v206
	v_add_f32_e32 v207, 1.0, v207
	v_rcp_f32_e32 v200, v200
	v_rcp_f32_e32 v201, v201
	v_rcp_f32_e32 v202, v202
	v_rcp_f32_e32 v203, v203
	v_rcp_f32_e32 v204, v204
	v_rcp_f32_e32 v205, v205
	v_rcp_f32_e32 v206, v206
	v_rcp_f32_e32 v207, v207
	v_pk_mul_f32 v[34:35], v[34:35], v[190:191] op_sel_hi:[1,0]
	v_pk_mul_f32 v[36:37], v[36:37], v[190:191] op_sel_hi:[1,0]
	v_pk_mul_f32 v[26:27], v[26:27], v[190:191] op_sel_hi:[1,0]
	v_pk_mul_f32 v[28:29], v[28:29], v[190:191] op_sel_hi:[1,0]
	v_mad_u64_u32 v[196:197], s[2:3], v150, s78, v[136:137]
	v_pk_mul_f32 v[34:35], v[34:35], v[200:201]
	v_pk_mul_f32 v[36:37], v[36:37], v[202:203]
	v_pk_mul_f32 v[26:27], v[26:27], v[204:205]
	v_pk_mul_f32 v[28:29], v[28:29], v[206:207]
	v_cvt_pk_bf16_f32 v192, v34, v35
	v_cvt_pk_bf16_f32 v193, v36, v37
	v_cvt_pk_bf16_f32 v194, v26, v27
	v_cvt_pk_bf16_f32 v195, v28, v29
	global_store_dwordx4 v[196:197], v[192:195], off
	v_mul_f32_e32 v188, 0xbfb8aa3b, v134
	v_mul_f32_e32 v190, v134, v134
	v_pk_mul_f32 v[200:201], v[18:19], v[188:189] op_sel_hi:[1,0]
	v_pk_mul_f32 v[202:203], v[20:21], v[188:189] op_sel_hi:[1,0]
	v_pk_mul_f32 v[204:205], v[6:7], v[188:189] op_sel_hi:[1,0]
	v_pk_mul_f32 v[206:207], v[8:9], v[188:189] op_sel_hi:[1,0]
	v_exp_f32_e32 v200, v200
	v_exp_f32_e32 v201, v201
	v_exp_f32_e32 v202, v202
	v_exp_f32_e32 v203, v203
	v_exp_f32_e32 v204, v204
	v_exp_f32_e32 v205, v205
	v_exp_f32_e32 v206, v206
	v_exp_f32_e32 v207, v207
	v_pk_mul_f32 v[18:19], v[18:19], v[10:11]
	v_pk_mul_f32 v[20:21], v[20:21], v[12:13]
	v_pk_mul_f32 v[6:7], v[6:7], v[2:3]
	v_pk_mul_f32 v[8:9], v[8:9], v[4:5]
	v_add_f32_e32 v200, 1.0, v200
	v_add_f32_e32 v201, 1.0, v201
	v_add_f32_e32 v202, 1.0, v202
	v_add_f32_e32 v203, 1.0, v203
	v_add_f32_e32 v204, 1.0, v204
	v_add_f32_e32 v205, 1.0, v205
	v_add_f32_e32 v206, 1.0, v206
	v_add_f32_e32 v207, 1.0, v207
	v_rcp_f32_e32 v200, v200
	v_rcp_f32_e32 v201, v201
	v_rcp_f32_e32 v202, v202
	v_rcp_f32_e32 v203, v203
	v_rcp_f32_e32 v204, v204
	v_rcp_f32_e32 v205, v205
	v_rcp_f32_e32 v206, v206
	v_rcp_f32_e32 v207, v207
	v_pk_mul_f32 v[18:19], v[18:19], v[190:191] op_sel_hi:[1,0]
	v_pk_mul_f32 v[20:21], v[20:21], v[190:191] op_sel_hi:[1,0]
	v_pk_mul_f32 v[6:7], v[6:7], v[190:191] op_sel_hi:[1,0]
	v_pk_mul_f32 v[8:9], v[8:9], v[190:191] op_sel_hi:[1,0]
	v_mad_u64_u32 v[196:197], s[2:3], v148, s78, v[136:137]
	v_pk_mul_f32 v[18:19], v[18:19], v[200:201]
	v_pk_mul_f32 v[20:21], v[20:21], v[202:203]
	v_pk_mul_f32 v[6:7], v[6:7], v[204:205]
	v_pk_mul_f32 v[8:9], v[8:9], v[206:207]
	v_cvt_pk_bf16_f32 v192, v18, v19
	v_cvt_pk_bf16_f32 v193, v20, v21
	v_cvt_pk_bf16_f32 v194, v6, v7
	v_cvt_pk_bf16_f32 v195, v8, v9
	global_store_dwordx4 v[196:197], v[192:195], off
	s_mov_b64 s[4:5], -1
	s_andn2_b64 vcc, exec, s[0:1]
	s_cbranch_vccnz .LBB0_889
	s_andn2_b64 vcc, exec, s[6:7]
	s_cbranch_vccnz .LBB0_888
	s_barrier
	s_branch .LBB0_888

	.amdhsa_kernel _Z14fwd_megakernel4Args
		.amdhsa_group_segment_fixed_size 0
		.amdhsa_private_segment_fixed_size 0
		.amdhsa_kernarg_size 440
		.amdhsa_user_sgpr_count 2
		.amdhsa_user_sgpr_dispatch_ptr 0
		.amdhsa_user_sgpr_queue_ptr 0
		.amdhsa_user_sgpr_kernarg_segment_ptr 1
		.amdhsa_user_sgpr_dispatch_id 0
		.amdhsa_user_sgpr_kernarg_preload_length 0
		.amdhsa_user_sgpr_kernarg_preload_offset 0
		.amdhsa_user_sgpr_private_segment_size 0
		.amdhsa_uses_dynamic_stack 0
		.amdhsa_enable_private_segment 0
		.amdhsa_system_sgpr_workgroup_id_x 1
		.amdhsa_system_sgpr_workgroup_id_y 0
		.amdhsa_system_sgpr_workgroup_id_z 0
		.amdhsa_system_sgpr_workgroup_info 0
		.amdhsa_system_vgpr_workitem_id 2
		.amdhsa_next_free_vgpr 256
		.amdhsa_next_free_sgpr 99
		.amdhsa_accum_offset 256
		.amdhsa_reserve_vcc 1
		.amdhsa_float_round_mode_32 0
		.amdhsa_float_round_mode_16_64 0
		.amdhsa_float_denorm_mode_32 3
		.amdhsa_float_denorm_mode_16_64 3
		.amdhsa_dx10_clamp 1
		.amdhsa_ieee_mode 1
		.amdhsa_fp16_overflow 0
		.amdhsa_tg_split 0
		.amdhsa_exception_fp_ieee_invalid_op 0
		.amdhsa_exception_fp_denorm_src 0
		.amdhsa_exception_fp_ieee_div_zero 0
		.amdhsa_exception_fp_ieee_overflow 0
		.amdhsa_exception_fp_ieee_underflow 0
		.amdhsa_exception_fp_ieee_inexact 0
		.amdhsa_exception_int_div_zero 0
	.end_amdhsa_kernel

amdhsa.kernels:
  - .agpr_count:     0
    .args:
      - .offset:         0
        .size:           184
        .value_kind:     by_value
      - .offset:         184
        .size:           4
        .value_kind:     hidden_block_count_x
      - .offset:         188
        .size:           4
        .value_kind:     hidden_block_count_y
      - .offset:         192
        .size:           4
        .value_kind:     hidden_block_count_z
      - .offset:         196
        .size:           2
        .value_kind:     hidden_group_size_x
      - .offset:         198
        .size:           2
        .value_kind:     hidden_group_size_y
      - .offset:         200
        .size:           2
        .value_kind:     hidden_group_size_z
      - .offset:         202
        .size:           2
        .value_kind:     hidden_remainder_x
      - .offset:         204
        .size:           2
        .value_kind:     hidden_remainder_y
      - .offset:         206
        .size:           2
        .value_kind:     hidden_remainder_z
      - .offset:         224
        .size:           8
        .value_kind:     hidden_global_offset_x
      - .offset:         232
        .size:           8
        .value_kind:     hidden_global_offset_y
      - .offset:         240
        .size:           8
        .value_kind:     hidden_global_offset_z
      - .offset:         248
        .size:           2
        .value_kind:     hidden_grid_dims
      - .offset:         272
        .size:           8
        .value_kind:     hidden_multigrid_sync_arg
      - .offset:         304
        .size:           4
        .value_kind:     hidden_dynamic_lds_size
    .group_segment_fixed_size: 0
    .kernarg_segment_align: 8
    .kernarg_segment_size: 440
    .language:       OpenCL C
    .language_version:
      - 2
      - 0
    .max_flat_workgroup_size: 512
    .name:           _Z14fwd_megakernel4Args
    .private_segment_fixed_size: 0
    .sgpr_count:     105
    .sgpr_spill_count: 111
    .symbol:         _Z14fwd_megakernel4Args.kd
    .uniform_work_group_size: 1
    .uses_dynamic_stack: false
    .vgpr_count:     256
    .vgpr_spill_count: 0
    .wavefront_size: 64
